# CV1: on top of MV2c: the 16 P packing v_cvt_pk moved from the end of the softmax section into the X section head behind its LDS reads (K fragments 1/2 renamed)
# baseline (speedup 1.0000x reference)
.LBB0_629:
	v_max_f32_e32 v148, v84, v85
	v_max_f32_e32 v149, v68, v69
	v_max3_f32 v148, v148, v86, v87
	v_max3_f32 v149, v149, v70, v71
	v_max3_f32 v148, v148, v88, v89
	v_max3_f32 v149, v149, v72, v73
	v_max3_f32 v148, v148, v90, v91
	v_max3_f32 v149, v149, v74, v75
	v_max3_f32 v148, v148, v92, v93
	v_max3_f32 v149, v149, v76, v77
	v_max3_f32 v148, v148, v94, v95
	v_max3_f32 v149, v149, v78, v79
	v_max3_f32 v148, v148, v96, v97
	v_max3_f32 v149, v149, v80, v81
	v_max3_f32 v148, v148, v98, v99
	v_max3_f32 v149, v149, v82, v83
	v_max_f32_e32 v148, v148, v149
	v_mov_b32_e32 v149, v148
	s_nop 1
	v_permlane32_swap_b32_e32 v148, v149
	v_max_f32_e32 v148, v148, v149
	v_sub_f32_e32 v149, v148, v182
	v_cmp_ge_f32_e32 vcc, s23, v149
	v_max_f32_e32 v148, v182, v148
	s_cmp_eq_u64 vcc, exec
	s_cselect_b64 vcc, -1, 0
	v_sub_f32_e32 v150, v182, v148
	v_cndmask_b32_e32 v182, v148, v182, vcc
	v_mul_f32_e32 v148, 0xbe0293ee, v182
	v_fmamk_f32 v84, v84, 0x3e0293ee, v148
	v_fmamk_f32 v85, v85, 0x3e0293ee, v148
	v_fmamk_f32 v86, v86, 0x3e0293ee, v148
	v_fmamk_f32 v87, v87, 0x3e0293ee, v148
	v_fmamk_f32 v88, v88, 0x3e0293ee, v148
	v_fmamk_f32 v89, v89, 0x3e0293ee, v148
	v_fmamk_f32 v90, v90, 0x3e0293ee, v148
	v_fmamk_f32 v91, v91, 0x3e0293ee, v148
	v_fmamk_f32 v92, v92, 0x3e0293ee, v148
	v_fmamk_f32 v93, v93, 0x3e0293ee, v148
	v_fmamk_f32 v94, v94, 0x3e0293ee, v148
	v_fmamk_f32 v95, v95, 0x3e0293ee, v148
	v_fmamk_f32 v96, v96, 0x3e0293ee, v148
	v_fmamk_f32 v97, v97, 0x3e0293ee, v148
	v_fmamk_f32 v98, v98, 0x3e0293ee, v148
	v_fmamk_f32 v99, v99, 0x3e0293ee, v148
	v_fmamk_f32 v68, v68, 0x3e0293ee, v148
	v_fmamk_f32 v69, v69, 0x3e0293ee, v148
	v_fmamk_f32 v70, v70, 0x3e0293ee, v148
	v_fmamk_f32 v71, v71, 0x3e0293ee, v148
	v_fmamk_f32 v72, v72, 0x3e0293ee, v148
	v_fmamk_f32 v73, v73, 0x3e0293ee, v148
	v_fmamk_f32 v74, v74, 0x3e0293ee, v148
	v_fmamk_f32 v75, v75, 0x3e0293ee, v148
	v_fmamk_f32 v76, v76, 0x3e0293ee, v148
	v_fmamk_f32 v77, v77, 0x3e0293ee, v148
	v_fmamk_f32 v78, v78, 0x3e0293ee, v148
	v_fmamk_f32 v79, v79, 0x3e0293ee, v148
	v_fmamk_f32 v80, v80, 0x3e0293ee, v148
	v_fmamk_f32 v81, v81, 0x3e0293ee, v148
	v_fmamk_f32 v82, v82, 0x3e0293ee, v148
	v_fmac_f32_e32 v148, 0x3e0293ee, v83
	v_exp_f32_e32 v83, v84
	v_exp_f32_e32 v84, v85
	v_exp_f32_e32 v85, v86
	v_add_f32_e32 v149, v84, v83
	v_exp_f32_e32 v86, v87
	v_add_f32_e32 v149, v85, v149
	v_exp_f32_e32 v87, v88
	v_add_f32_e32 v149, v86, v149
	v_exp_f32_e32 v88, v89
	v_add_f32_e32 v149, v87, v149
	v_exp_f32_e32 v89, v90
	v_add_f32_e32 v149, v88, v149
	v_exp_f32_e32 v90, v91
	v_add_f32_e32 v149, v89, v149
	v_exp_f32_e32 v91, v92
	v_add_f32_e32 v149, v90, v149
	v_exp_f32_e32 v92, v93
	v_add_f32_e32 v149, v91, v149
	v_exp_f32_e32 v93, v94
	v_add_f32_e32 v149, v92, v149
	v_exp_f32_e32 v94, v95
	v_add_f32_e32 v149, v93, v149
	v_exp_f32_e32 v95, v96
	v_add_f32_e32 v149, v94, v149
	v_exp_f32_e32 v96, v97
	v_add_f32_e32 v149, v95, v149
	v_exp_f32_e32 v97, v98
	v_add_f32_e32 v149, v96, v149
	v_exp_f32_e32 v98, v99
	v_add_f32_e32 v149, v97, v149
	v_exp_f32_e32 v99, v148
	v_add_f32_e32 v149, v98, v149
	v_exp_f32_e32 v68, v68
	v_exp_f32_e32 v69, v69
	v_add_f32_e32 v149, v68, v149
	v_exp_f32_e32 v70, v70
	v_add_f32_e32 v149, v69, v149
	v_exp_f32_e32 v71, v71
	v_add_f32_e32 v149, v70, v149
	v_exp_f32_e32 v72, v72
	v_add_f32_e32 v149, v71, v149
	v_exp_f32_e32 v73, v73
	v_add_f32_e32 v149, v72, v149
	v_exp_f32_e32 v74, v74
	v_add_f32_e32 v149, v73, v149
	v_exp_f32_e32 v75, v75
	v_add_f32_e32 v149, v74, v149
	v_exp_f32_e32 v76, v76
	v_add_f32_e32 v149, v75, v149
	v_exp_f32_e32 v77, v77
	v_add_f32_e32 v149, v76, v149
	v_exp_f32_e32 v78, v78
	v_add_f32_e32 v149, v77, v149
	v_exp_f32_e32 v79, v79
	v_add_f32_e32 v149, v78, v149
	v_exp_f32_e32 v80, v80
	v_add_f32_e32 v149, v79, v149
	v_exp_f32_e32 v81, v81
	v_add_f32_e32 v149, v80, v149
	v_exp_f32_e32 v82, v82
	v_add_f32_e32 v149, v81, v149
	v_mul_f32_e32 v150, 0x3e0293ee, v150
	v_add_f32_e32 v149, v82, v149
	v_exp_f32_e32 v150, v150
	v_add_f32_e32 v185, v99, v149
	v_cndmask_b32_e64 v184, v150, 1.0, vcc
	s_mov_b32 s53, s52
	s_cbranch_vccnz .LBB0_633
	v_cvt_pk_bf16_f32 v148, v83, v84
	v_cvt_pk_bf16_f32 v149, v85, v86
	v_cvt_pk_bf16_f32 v150, v87, v88
	v_cvt_pk_bf16_f32 v151, v89, v90
	v_cvt_pk_bf16_f32 v152, v91, v92
	v_cvt_pk_bf16_f32 v153, v93, v94
	v_cvt_pk_bf16_f32 v154, v95, v96
	v_cvt_pk_bf16_f32 v155, v97, v98
	v_cvt_pk_bf16_f32 v156, v68, v69
	v_cvt_pk_bf16_f32 v157, v70, v71
	v_cvt_pk_bf16_f32 v158, v72, v73
	v_cvt_pk_bf16_f32 v159, v74, v75
	v_cvt_pk_bf16_f32 v160, v76, v77
	v_cvt_pk_bf16_f32 v161, v78, v79
	v_cvt_pk_bf16_f32 v162, v80, v81
	v_cvt_pk_bf16_f32 v163, v82, v99
	s_and_saveexec_b64 s[16:17], s[38:39]
	ds_write_b32 v172, v184 offset:128
	s_or_b64 exec, exec, s[16:17]
	s_waitcnt lgkmcnt(0)
	v_add_u32_e32 v80, v171, v168
	ds_read_b128 v[68:71], v80 offset:224
	ds_read_b128 v[72:75], v80 offset:192
	ds_read_b128 v[76:79], v80 offset:160
	ds_read_b128 v[80:83], v80 offset:128
	s_waitcnt lgkmcnt(3)
	v_pk_mul_f32 v[16:17], v[16:17], v[68:69]
	s_waitcnt lgkmcnt(2)
	v_pk_mul_f32 v[12:13], v[12:13], v[72:73]
	s_waitcnt lgkmcnt(1)
	v_pk_mul_f32 v[8:9], v[8:9], v[76:77]
	v_pk_mul_f32 v[18:19], v[18:19], v[70:71]
	v_pk_mul_f32 v[14:15], v[14:15], v[74:75]
	v_pk_mul_f32 v[10:11], v[10:11], v[78:79]
	s_waitcnt lgkmcnt(0)
	v_pk_mul_f32 v[6:7], v[6:7], v[82:83]
	v_pk_mul_f32 v[4:5], v[4:5], v[80:81]
	v_pk_mul_f32 v[64:65], v[64:65], v[68:69]
	v_pk_mul_f32 v[60:61], v[60:61], v[72:73]
	v_pk_mul_f32 v[56:57], v[56:57], v[76:77]
	v_pk_mul_f32 v[66:67], v[66:67], v[70:71]
	v_pk_mul_f32 v[62:63], v[62:63], v[74:75]
	v_pk_mul_f32 v[58:59], v[58:59], v[78:79]
	v_pk_mul_f32 v[54:55], v[54:55], v[82:83]
	v_pk_mul_f32 v[52:53], v[52:53], v[80:81]
	v_pk_mul_f32 v[48:49], v[48:49], v[68:69]
	v_pk_mul_f32 v[44:45], v[44:45], v[72:73]
	v_pk_mul_f32 v[40:41], v[40:41], v[76:77]
	v_pk_mul_f32 v[50:51], v[50:51], v[70:71]
	v_pk_mul_f32 v[46:47], v[46:47], v[74:75]
	v_pk_mul_f32 v[42:43], v[42:43], v[78:79]
	v_pk_mul_f32 v[38:39], v[38:39], v[82:83]
	v_pk_mul_f32 v[36:37], v[36:37], v[80:81]
	v_pk_mul_f32 v[32:33], v[32:33], v[68:69]
	v_pk_mul_f32 v[28:29], v[28:29], v[72:73]
	v_pk_mul_f32 v[24:25], v[24:25], v[76:77]
	v_pk_mul_f32 v[34:35], v[34:35], v[70:71]
	v_pk_mul_f32 v[30:31], v[30:31], v[74:75]
	v_pk_mul_f32 v[26:27], v[26:27], v[78:79]
	v_pk_mul_f32 v[22:23], v[22:23], v[82:83]
	v_pk_mul_f32 v[20:21], v[20:21], v[80:81]
.Lmy_x_resc:
	s_waitcnt lgkmcnt(0)
	s_barrier
	v_lshl_add_u32 v187, s53, 14, v173
	ds_read_b64_tr_b16 v[188:189], v187 offset:0
	ds_read_b64_tr_b16 v[190:191], v187 offset:0x800
	ds_read_b64_tr_b16 v[192:193], v187 offset:0x1000
	ds_read_b64_tr_b16 v[194:195], v187 offset:0x1800
	ds_read_b64_tr_b16 v[196:197], v187 offset:0x2000
	ds_read_b64_tr_b16 v[198:199], v187 offset:0x2800
	ds_read_b64_tr_b16 v[200:201], v187 offset:0x3000
	ds_read_b64_tr_b16 v[202:203], v187 offset:0x3800
	s_lshl_b32 s52, s49, 14
	v_add_u32_e32 v208, s52, v174
	ds_read_b128 v[236:239], v208 offset:0
	ds_read_b128 v[242:245], v208 offset:0x2000
	v_add_u32_e32 v209, s52, v175
	ds_read_b128 v[204:207], v209 offset:0
	ds_read_b128 v[216:219], v209 offset:0x2000
	v_add_u32_e32 v210, s52, v176
	ds_read_b128 v[220:223], v210 offset:0
	ds_read_b128 v[224:227], v210 offset:0x2000
	v_add_u32_e32 v211, s52, v177
	ds_read_b128 v[228:231], v211 offset:0
	ds_read_b128 v[232:235], v211 offset:0x2000
	s_branch .Lmy_x_join
.LBB0_633:
	s_waitcnt lgkmcnt(0)
	s_barrier
	v_lshl_add_u32 v187, s53, 14, v173
	ds_read_b64_tr_b16 v[188:189], v187 offset:0
	ds_read_b64_tr_b16 v[190:191], v187 offset:0x800
	ds_read_b64_tr_b16 v[192:193], v187 offset:0x1000
	ds_read_b64_tr_b16 v[194:195], v187 offset:0x1800
	ds_read_b64_tr_b16 v[196:197], v187 offset:0x2000
	ds_read_b64_tr_b16 v[198:199], v187 offset:0x2800
	ds_read_b64_tr_b16 v[200:201], v187 offset:0x3000
	ds_read_b64_tr_b16 v[202:203], v187 offset:0x3800
	s_lshl_b32 s52, s49, 14
	v_add_u32_e32 v208, s52, v174
	ds_read_b128 v[236:239], v208 offset:0
	ds_read_b128 v[242:245], v208 offset:0x2000
	v_add_u32_e32 v209, s52, v175
	ds_read_b128 v[204:207], v209 offset:0
	ds_read_b128 v[216:219], v209 offset:0x2000
	v_add_u32_e32 v210, s52, v176
	ds_read_b128 v[220:223], v210 offset:0
	ds_read_b128 v[224:227], v210 offset:0x2000
	v_add_u32_e32 v211, s52, v177
	ds_read_b128 v[228:231], v211 offset:0
	ds_read_b128 v[232:235], v211 offset:0x2000
	v_cvt_pk_bf16_f32 v148, v83, v84
	v_cvt_pk_bf16_f32 v149, v85, v86
	v_cvt_pk_bf16_f32 v150, v87, v88
	v_cvt_pk_bf16_f32 v151, v89, v90
	v_cvt_pk_bf16_f32 v152, v91, v92
	v_cvt_pk_bf16_f32 v153, v93, v94
	v_cvt_pk_bf16_f32 v154, v95, v96
	v_cvt_pk_bf16_f32 v155, v97, v98
	v_cvt_pk_bf16_f32 v156, v68, v69
	v_cvt_pk_bf16_f32 v157, v70, v71
	v_cvt_pk_bf16_f32 v158, v72, v73
	v_cvt_pk_bf16_f32 v159, v74, v75
	v_cvt_pk_bf16_f32 v160, v76, v77
	v_cvt_pk_bf16_f32 v161, v78, v79
	v_cvt_pk_bf16_f32 v162, v80, v81
	v_cvt_pk_bf16_f32 v163, v82, v99
.Lmy_x_join:
	s_waitcnt lgkmcnt(4)
	v_mfma_f32_32x32x16_bf16 v[84:99], v[236:239], v[128:131], 0
	v_mfma_f32_32x32x16_bf16 v[68:83], v[242:245], v[128:131], 0
	v_mfma_f32_32x32x16_bf16 v[84:99], v[204:207], v[124:127], v[84:99]
	v_mfma_f32_32x32x16_bf16 v[68:83], v[216:219], v[124:127], v[68:83]
	ds_read_b128 v[204:207], v208 offset:0x80
	ds_read_b128 v[216:219], v208 offset:0x2080
	ds_read_b128 v[236:239], v209 offset:0x80
	ds_read_b128 v[242:245], v209 offset:0x2080
	s_waitcnt lgkmcnt(4)
	v_mfma_f32_32x32x16_bf16 v[84:99], v[220:223], v[120:123], v[84:99]
	v_mfma_f32_32x32x16_bf16 v[68:83], v[224:227], v[120:123], v[68:83]
	v_mfma_f32_32x32x16_bf16 v[84:99], v[228:231], v[116:119], v[84:99]
	v_mfma_f32_32x32x16_bf16 v[68:83], v[232:235], v[116:119], v[68:83]
	ds_read_b128 v[220:223], v210 offset:0x80
	ds_read_b128 v[224:227], v210 offset:0x2080
	ds_read_b128 v[228:231], v211 offset:0x80
	ds_read_b128 v[232:235], v211 offset:0x2080
	s_waitcnt lgkmcnt(4)
	v_mfma_f32_32x32x16_bf16 v[84:99], v[204:207], v[112:115], v[84:99]
	v_mfma_f32_32x32x16_bf16 v[68:83], v[216:219], v[112:115], v[68:83]
	v_mfma_f32_32x32x16_bf16 v[84:99], v[236:239], v[108:111], v[84:99]
	v_mfma_f32_32x32x16_bf16 v[68:83], v[242:245], v[108:111], v[68:83]
	s_waitcnt lgkmcnt(0)
	v_mfma_f32_32x32x16_bf16 v[84:99], v[220:223], v[104:107], v[84:99]
	v_mfma_f32_32x32x16_bf16 v[68:83], v[224:227], v[104:107], v[68:83]
	v_mfma_f32_32x32x16_bf16 v[84:99], v[228:231], v[100:103], v[84:99]
	v_mfma_f32_32x32x16_bf16 v[68:83], v[232:235], v[100:103], v[68:83]
	ds_read_b64_tr_b16 v[204:205], v187 offset:0x200
	ds_read_b64_tr_b16 v[206:207], v187 offset:0xa00
	ds_read_b64_tr_b16 v[216:217], v187 offset:0x1200
	ds_read_b64_tr_b16 v[218:219], v187 offset:0x1a00
	ds_read_b64_tr_b16 v[220:221], v187 offset:0x2200
	ds_read_b64_tr_b16 v[222:223], v187 offset:0x2a00
	ds_read_b64_tr_b16 v[224:225], v187 offset:0x3200
	ds_read_b64_tr_b16 v[226:227], v187 offset:0x3a00
	s_waitcnt lgkmcnt(8)
	v_mfma_f32_32x32x16_bf16 v[4:19], v[148:151], v[188:191], v[4:19]
	s_lshl_b32 s19, s51, 14
	s_add_i32 s8, s19, 0
	v_add_u32_e32 v236, s8, v179
	s_waitcnt vmcnt(0)
	v_mfma_f32_32x32x16_bf16 v[4:19], v[152:155], v[192:195], v[4:19]
	ds_write_b128 v236, v[144:147]
	v_add_u32_e32 v236, s8, v178
	v_mfma_f32_32x32x16_bf16 v[4:19], v[156:159], v[196:199], v[4:19]
	ds_write_b128 v236, v[136:139]
	v_add_u32_e32 v236, s8, v180
	v_mfma_f32_32x32x16_bf16 v[4:19], v[160:163], v[200:203], v[4:19]
	ds_read_b64_tr_b16 v[188:189], v187 offset:0x400
	ds_read_b64_tr_b16 v[190:191], v187 offset:0xc00
	ds_read_b64_tr_b16 v[192:193], v187 offset:0x1400
	ds_read_b64_tr_b16 v[194:195], v187 offset:0x1c00
	ds_read_b64_tr_b16 v[196:197], v187 offset:0x2400
	ds_read_b64_tr_b16 v[198:199], v187 offset:0x2c00
	ds_read_b64_tr_b16 v[200:201], v187 offset:0x3400
	ds_read_b64_tr_b16 v[202:203], v187 offset:0x3c00
	s_waitcnt lgkmcnt(10)
	v_mfma_f32_32x32x16_bf16 v[52:67], v[148:151], v[204:207], v[52:67]
	ds_write_b128 v236, v[140:143] offset:49152
	v_add_u32_e32 v236, s8, v181
	v_mfma_f32_32x32x16_bf16 v[52:67], v[152:155], v[216:219], v[52:67]
	ds_write_b128 v236, v[132:135] offset:49152
	s_add_i32 s48, s48, 1
	v_mfma_f32_32x32x16_bf16 v[52:67], v[156:159], v[220:223], v[52:67]
	s_sub_i32 s8, s50, s47
	s_min_u32 s36, s50, s8
	s_lshl_b64 s[8:9], s[36:37], 10
	s_cmp_lt_u32 s50, s47
	s_cselect_b32 s16, s30, s20
	s_cselect_b32 s17, s31, s21
	v_mfma_f32_32x32x16_bf16 v[52:67], v[160:163], v[224:227], v[52:67]
	ds_read_b64_tr_b16 v[204:205], v187 offset:0x600
	ds_read_b64_tr_b16 v[206:207], v187 offset:0xe00
	ds_read_b64_tr_b16 v[216:217], v187 offset:0x1600
	ds_read_b64_tr_b16 v[218:219], v187 offset:0x1e00
	ds_read_b64_tr_b16 v[220:221], v187 offset:0x2600
	ds_read_b64_tr_b16 v[222:223], v187 offset:0x2e00
	ds_read_b64_tr_b16 v[224:225], v187 offset:0x3600
	ds_read_b64_tr_b16 v[226:227], v187 offset:0x3e00
	s_cselect_b32 s36, s42, s26
	s_cselect_b32 s54, s43, s27
	s_add_u32 s16, s16, s8
	s_addc_u32 s17, s17, s9
	s_add_u32 s8, s36, s8
	s_addc_u32 s9, s54, s9
	s_waitcnt lgkmcnt(0)
